# baseline (speedup 1.0000x reference)
; #define LAS __attribute__((address_space(3)))
; __device__ __forceinline__ KArgs get_args() { KArgs p = (KArgs)__builtin_amdgcn_kernarg_segment_ptr(); asm volatile("" : "+s"(p)); return p; }
; #define a (*get_args())
; __device__ __forceinline__ void attn_fast(KArgs ap, int l, LAS unsigned char* lds, const Ctx cx) {
;     const int wave = cx.wave, lane = cx.lane;
;     const auto& a = *ap;
;     const bf16_t* z = (const bf16_t*)(a.ws + WS_Z); bf16_t* y = (bf16_t*)(a.ws + WS_Y);
;     const float* sinks = a.in[I_SINKS] + l * 16;
;     LAS unsigned char* KL = lds;
;     LAS unsigned char* VTL = lds + 36864;
;     const int tid = cx.tid, r = lane & 31, hh = lane >> 5;
;     for (int u = cx.bid; u < BATCH * (SEQ / 128) * 2; u += cx.nb) {
;         const int kvh = u & 1, nbk = u >> 1, nb = nbk & 127;
;         const size_t tok0 = (size_t)nbk * 128;
;         __syncthreads();
; #pragma unroll
;         for (int i = 0; i < 4; ++i) { const int idx = tid + 512 * i, key = idx >> 3, ch = idx & 7;
;             u32x4 v = (u32x4){0u, 0u, 0u, 0u};
;             if (nb > 0 || key >= 128) v = *(const u32x4*)(z + (tok0 - 128 + key) * DIN + ZK + kvh * 64 + ch * 8);
; __global__ void __launch_bounds__(512, 2) mega(Args a_unused) {
;     ...
;         if (RUN(pb + 2)) { const Ctx cx = mkctx();
;             for (int rep = 0; rep < ((l == 0 && REP_PHASE == 21) ? REP_N + 1 : 1); ++rep) attn_fast(get_args(), l, lds, cx);
.LBB0_117:
.LBB0_118:
	s_mov_b64 s[0:1], s[78:79]
	s_load_dword s1, s[0:1], 0xe0
	s_mul_i32 s4, s62, 11
	s_lshl_b32 s5, s62, 20
	s_add_i32 s0, s4, 3
	v_writelane_b32 v243, s5, 19
	s_add_i32 s4, s4, 4
	s_lshl_b32 s6, s62, 9
	v_writelane_b32 v243, s4, 20
	s_mov_b32 s7, s77
	s_waitcnt lgkmcnt(0)
	s_cmp_gt_i32 s1, s0
	v_writelane_b32 v243, s6, 21
	s_nop 1
	v_writelane_b32 v243, s7, 22
	s_cbranch_scc1 .LBB0_235
	s_mov_b64 s[4:5], s[78:79]
	s_load_dword s1, s[4:5], 0xe4
	s_waitcnt lgkmcnt(0)
	s_cmp_ge_i32 s0, s1
	s_cbranch_scc1 .LBB0_235
	v_readfirstlane_b32 s4, v192
	s_nop 3
	s_lshr_b32 s4, s4, 6
	s_cmp_ge_u32 s4, 4
	s_cbranch_scc0 .Lprio_skip_mix
	s_setprio 1
.Lprio_skip_mix:
	v_readlane_b32 s0, v243, 0
	s_mov_b32 s57, s0
	v_readlane_b32 s0, v243, 5
	v_mov_b32_e32 v0, v192
	v_readlane_b32 s1, v243, 6
	s_load_dword s55, s[0:1], 0x0
	v_bfe_u32 v87, v0, 5, 1
	v_readfirstlane_b32 s6, v0
	s_cmpk_lt_i32 s57, 0x200
	v_lshlrev_b32_e32 v84, 3, v87
	s_mov_b64 s[0:1], s[78:79]
	s_mov_b64 s[4:5], -1
	s_waitcnt lgkmcnt(0)
	v_writelane_b32 v243, s55, 23
	s_cbranch_scc1 .LBB0_122
	v_mov_b32_e32 v85, v153
	s_mov_b64 s[4:5], 0

; template <bool OUT>
; __device__ __forceinline__ void ssm_fast(KArgs ap, int l, LAS unsigned char* lds, const Ctx cx) {
;     const int wave = cx.wave, lane = cx.lane;
;     const auto& a = *ap;
;     const bf16_t* z = (const bf16_t*)(a.ws + WS_Z); bf16_t* ypre = (bf16_t*)(a.ws + WS_YPRE); float* E = (float*)(a.ws + WS_E);
;     const unsigned char* tb = a.ws + WS_TAB + (size_t)l * TAB_STRIDE;
;     const int gw = cx.bid * 8 + wave, NGW = cx.nb * 8;
;     const int g = gw & 31, r = lane & 31, hh = lane >> 5, p = lane;
;     LAS unsigned char* BU = lds + wave * 16384;
;     const float are = ((const float*)(tb + TAB_A))[(g * 64 + p) * 2], aim = ((const float*)(tb + TAB_A))[(g * 64 + p) * 2 + 1];
;     bf16x8 bt[4];
; #pragma unroll
;     for (int nb = 0; nb < 4; ++nb) bt[nb] = *(const bf16x8*)((const bf16_t*)(tb + TAB_BT) + (g * 128 + nb * 32 + r) * 16 + 8 * hh);
;     bf16x8 ct[4]; float dsk = 0.f;
;     if (OUT) {
; #pragma unroll
;         for (int ks = 0; ks < 4; ++ks) ct[ks] = *(const bf16x8*)((const bf16_t*)(tb + TAB_CT) + (g * 16 + (lane & 15)) * 128 + ks * 32 + 8 * (lane >> 4));
;         dsk = a.in[I_SSM_D][l * 512 + g * 16 + (lane & 15)];
;     }
;     __syncthreads();
; #pragma unroll 1
;     for (int it = gw; it < BATCH * SSM_NC * 32; it += NGW) {
;         const size_t tok0 = (size_t)(it >> 5) * 128;
;         float sr = 0.f, si = 0.f;
;         if (OUT) { sr = E[(size_t)it * 128 + p]; si = E[(size_t)it * 128 + 64 + p]; }
; #pragma unroll 1
;         for (int sc = 0; sc < 4; ++sc) {
;             const size_t tk = tok0 + sc * 32;
;             const bf16x8 uf = *(const bf16x8*)(z + (tk + r) * DIN + ZS + g * 16 + 8 * hh);
;             bf16_t uv[2][4];
;             if (OUT) {
; #pragma unroll
;                 for (int tbk = 0; tbk < 2; ++tbk)
; #pragma unroll
;                     for (int j = 0; j < 4; ++j) uv[tbk][j] = z[(tk + tbk * 16 + 4 * (lane >> 4) + j) * DIN + ZS + g * 16 + (lane & 15)];
;             }
;             WAVE_FENCE();
; #pragma unroll
;             for (int nb = 0; nb < 4; ++nb) { f32x16 c;
; #pragma unroll
;                 for (int i = 0; i < 16; ++i) c[i] = 0.f;
; __global__ void __launch_bounds__(512, 2) mega(Args a_unused) {
;     ...
;         if (RUN(pb + 4)) { const Ctx cx = mkctx();
;             for (int rep = 0; rep < ((l == 0 && REP_PHASE == 24) ? REP_N + 1 : 1); ++rep) ssm_fast<true>(get_args(), l, lds, cx);
.LBB0_305:
.LBB0_306:
	s_mov_b64 s[0:1], s[78:79]
	s_load_dword s0, s[0:1], 0xe0
	v_readlane_b32 s1, v243, 18
	s_add_i32 s56, s1, 6
	s_waitcnt lgkmcnt(0)
	s_cmp_gt_i32 s0, s55
	s_cbranch_scc1 .LBB0_376
	s_mov_b64 s[0:1], s[78:79]
	s_load_dword s0, s[0:1], 0xe4
	s_waitcnt lgkmcnt(0)
	s_cmp_ge_i32 s55, s0
	s_cbranch_scc1 .LBB0_376
	v_readfirstlane_b32 s4, v192
	s_nop 3
	s_lshr_b32 s4, s4, 6
	s_cmp_ge_u32 s4, 4
	s_cbranch_scc0 .Lprio_skip_ssmc
	s_setprio 1
.Lprio_skip_ssmc:
	v_readlane_b32 s4, v243, 5
	v_mov_b32_e32 v8, v192
	v_readlane_b32 s0, v243, 0
	v_readlane_b32 s5, v243, 6
	s_load_dword s6, s[4:5], 0x0
	v_readfirstlane_b32 s1, v8
	s_ashr_i32 s8, s1, 6
	s_lshl_b32 s0, s0, 3
	s_add_i32 s0, s8, s0
	s_waitcnt lgkmcnt(0)
	s_mov_b32 s7, s6
	s_mov_b64 s[10:11], s[78:79]
	v_and_b32_e32 v2, 63, v8
	s_and_b32 s9, s0, 31
	s_load_dwordx2 s[4:5], s[10:11], 0xd8
	v_and_b32_e32 v96, 31, v8
	s_lshl_b32 s1, s9, 7
	v_lshlrev_b32_e32 v3, 1, v2
	v_or_b32_e32 v4, s1, v3
	v_or_b32_e32 v6, s1, v96
	s_lshl_b32 s1, s9, 4
	v_readlane_b32 s12, v243, 21
	s_or_b32 s12, s1, s12
	v_and_b32_e32 v0, 15, v8
	v_or_b32_e32 v152, s12, v0
	v_readlane_b32 s12, v243, 19
	v_readlane_b32 s13, v243, 22
	s_waitcnt lgkmcnt(0)
	s_add_u32 s12, s4, s12
	s_addc_u32 s13, s5, 0
	v_bfe_u32 v1, v8, 5, 1
	s_add_u32 s12, s12, 0x3e600000
	s_addc_u32 s13, s13, 0
	v_lshlrev_b32_e32 v9, 2, v4
	v_lshlrev_b32_e32 v4, 4, v1
	v_mov_b32_e32 v5, v153
	v_lshl_add_u64 v[4:5], s[12:13], 0, v[4:5]
	v_lshlrev_b32_e32 v6, 5, v6
	v_mov_b32_e32 v7, v153
	v_lshl_add_u64 v[4:5], v[4:5], 0, v[6:7]
	s_mov_b64 s[14:15], 0x8000
	v_lshl_add_u64 v[6:7], v[4:5], 0, s[14:15]
	s_load_dwordx2 s[10:11], s[10:11], 0x58
	global_load_dwordx2 v[98:99], v9, s[12:13]
	global_load_dwordx4 v[64:67], v[6:7], off offset:1024
	global_load_dwordx4 v[68:71], v[6:7], off offset:2048
	global_load_dwordx4 v[72:75], v[6:7], off offset:3072
	v_lshlrev_b32_e32 v6, 8, v8
	v_and_b32_e32 v6, 0xf00, v6
	s_mov_b32 s14, 0x8000
	v_lshl_or_b32 v6, s9, 12, v6
	v_mov_b32_e32 v7, v153
	v_add_co_u32_e32 v4, vcc, s14, v4
	v_lshl_add_u64 v[6:7], s[12:13], 0, v[6:7]
	v_and_b32_e32 v8, 48, v8
	v_mov_b32_e32 v9, v153
	v_addc_co_u32_e32 v5, vcc, 0, v5, vcc
	v_lshl_add_u64 v[6:7], v[6:7], 0, v[8:9]
	s_mov_b64 s[12:13], 0x28000
	v_lshl_add_u64 v[8:9], v[6:7], 0, s[12:13]
	v_add_co_u32_e32 v6, vcc, 0x28000, v6
	s_cmpk_gt_i32 s0, 0x1fff
	s_nop 0
	v_addc_co_u32_e32 v7, vcc, 0, v7, vcc
	global_load_dwordx4 v[76:79], v[6:7], off
	global_load_dwordx4 v[80:83], v[4:5], off
	global_load_dwordx4 v[84:87], v[8:9], off offset:64
	global_load_dwordx4 v[88:91], v[8:9], off offset:128
	global_load_dwordx4 v[92:95], v[8:9], off offset:192
	s_waitcnt lgkmcnt(0)
	v_lshl_add_u64 v[4:5], v[152:153], 2, s[10:11]
	global_load_dword v97, v[4:5], off
	s_waitcnt vmcnt(0)
	s_barrier
	s_cbranch_scc1 .LBB0_315
	s_lshl_b32 s8, s8, 14
	v_lshlrev_b32_e32 v4, 3, v1
	s_add_i32 s10, s8, 0
	v_lshrrev_b32_e32 v5, 2, v2
	v_lshlrev_b32_e32 v152, 2, v2
	v_lshrrev_b32_e32 v103, 3, v2
	v_and_b32_e32 v6, 14, v3
	v_lshrrev_b32_e32 v2, 4, v2
	v_lshlrev_b32_e32 v1, 11, v1
	v_lshlrev_b32_e32 v3, 2, v96
	v_add3_u32 v107, s10, v1, v3
	v_xor_b32_e32 v1, v2, v0
	v_and_b32_e32 v100, 12, v5
	v_or_b32_e32 v110, 3, v5
	v_or_b32_e32 v118, 19, v5
	v_lshlrev_b32_e32 v5, 4, v1
	v_bitop3_b32 v1, v2, v0, 4 bitop3:0x36
	v_lshlrev_b32_e32 v8, 4, v1
	v_bitop3_b32 v1, v2, v0, 8 bitop3:0x36
	s_lshl_b32 s7, s7, 3
	v_lshlrev_b32_e32 v102, 2, v2
	v_lshlrev_b32_e32 v9, 4, v1
	v_bitop3_b32 v1, v2, v0, 12 bitop3:0x36
	v_lshl_add_u64 v[2:3], s[4:5], 0, v[152:153]
	s_mov_b64 s[8:9], 0x3e000000
	s_lshl_b32 s1, s1, 1
	v_lshl_add_u64 v[132:133], v[2:3], 0, s[8:9]
	s_add_u32 s8, s4, s1
	s_addc_u32 s9, s5, 0
	s_add_u32 s1, s4, s1
	v_add_u32_e32 v101, s10, v152
	v_lshlrev_b32_e32 v152, 1, v0
	s_addc_u32 s5, s5, 0
	v_lshl_add_u32 v7, v0, 9, s10
	v_lshlrev_b32_e32 v10, 4, v1
	v_lshl_add_u64 v[0:1], s[8:9], 0, v[152:153]
	s_mov_b64 s[8:9], 0x3c000000
	s_add_u32 s4, s1, 0x13000000
	v_lshl_add_u64 v[134:135], v[0:1], 0, s[8:9]
	s_addc_u32 s5, s5, 0
	v_lshlrev_b32_e32 v0, 1, v4
	v_mov_b32_e32 v1, v153
	v_or_b32_e32 v105, 8, v103
	v_or_b32_e32 v104, 16, v102
	v_or_b32_e32 v106, 1, v100
	v_or_b32_e32 v108, 2, v100
	v_or_b32_e32 v112, 16, v100
	v_or_b32_e32 v114, 17, v100
	v_or_b32_e32 v116, 18, v100
	v_or_b32_e32 v120, 1, v102
	v_or_b32_e32 v122, 2, v102
	v_or_b32_e32 v124, 3, v102
	v_or_b32_e32 v126, 17, v102
	v_or_b32_e32 v128, 18, v102
	v_or_b32_e32 v130, 19, v102
	v_pk_mov_b32 v[136:137], v[98:99], v[98:99] op_sel:[1,0]
	v_lshl_add_u64 v[138:139], s[4:5], 0, v[0:1]
	v_lshl_add_u64 v[140:141], s[4:5], 0, v[152:153]
	v_add_u32_e32 v109, s10, v6
	v_add_u32_e32 v111, v7, v5
	v_add_u32_e32 v113, v7, v8
	v_add_u32_e32 v115, v7, v9
	v_add_u32_e32 v117, v7, v10
	s_mov_b32 s58, 0x2c000
	s_mov_b32 s59, 0
	v_xor_b32_e32 v215, 0, v103
	v_lshl_add_u32 v199, v215, 4, v109
	v_xor_b32_e32 v215, 1, v103
	v_lshl_add_u32 v200, v215, 4, v109
	v_xor_b32_e32 v215, 2, v103
	v_lshl_add_u32 v201, v215, 4, v109
	v_xor_b32_e32 v215, 3, v103
	v_lshl_add_u32 v202, v215, 4, v109
	v_xor_b32_e32 v215, 4, v103
	v_lshl_add_u32 v203, v215, 4, v109
	v_xor_b32_e32 v215, 5, v103
	v_lshl_add_u32 v204, v215, 4, v109
	v_xor_b32_e32 v215, 6, v103
	v_lshl_add_u32 v205, v215, 4, v109
	v_xor_b32_e32 v215, 7, v103
	v_lshl_add_u32 v206, v215, 4, v109
	v_xor_b32_e32 v215, 8, v103
	v_lshl_add_u32 v207, v215, 4, v109
	v_xor_b32_e32 v215, 9, v103
	v_lshl_add_u32 v208, v215, 4, v109
	v_xor_b32_e32 v215, 10, v103
	v_lshl_add_u32 v209, v215, 4, v109
	v_xor_b32_e32 v215, 11, v103
	v_lshl_add_u32 v210, v215, 4, v109
	v_xor_b32_e32 v215, 12, v103
	v_lshl_add_u32 v211, v215, 4, v109
	v_xor_b32_e32 v215, 13, v103
	v_lshl_add_u32 v212, v215, 4, v109
	v_xor_b32_e32 v215, 14, v103
	v_lshl_add_u32 v213, v215, 4, v109
	v_xor_b32_e32 v215, 15, v103
	v_lshl_add_u32 v214, v215, 4, v109
